# idle-tail helper: WGs 128-255 (one GEMM tile fewer in w13 and in-proj phases) run the next prep phase weight conversion in their idle tail; prep phases s=3,9 skip conversion
# baseline (speedup 1.0000x reference)
; #define PG8_LAS __attribute__((address_space(3)))
; __global__ void __launch_bounds__(512, 2) mega_fwd(Params p) {
;     extern __shared__ __attribute__((aligned(16))) unsigned char lds_raw[];
;     const int G0 = gridDim.x, bx0 = blockIdx.x, wv0 = __builtin_amdgcn_readfirstlane((int)(threadIdx.x >> 6)); unsigned nbar = 0;
;     ...
;     for (int phx = p.ph_lo * (1 + REP_N); phx < p.ph_hi * (1 + REP_N); ++phx) {
;         const int ph = phx / (1 + REP_N);
;         if (REP_N > 0 && (phx % (1 + REP_N)) != 0 && !(ph > 0 && (ph - 1) % 12 == REP_S && (REP_L < 0 || (ph - 1) / 12 == REP_L))) continue;
;         if (phx > p.ph_lo * (1 + REP_N)) {
;             if (phx == p.ph_lo * (1 + REP_N) + 1) cg::this_grid().sync();
;             else { ++nbar; fast_grid_barrier((unsigned*)(p.ws + OFF_CTR), nbar * (unsigned)G0); }
;         }
;     ...
;         if ((phx % (1 + REP_N)) != 0) continue;
;     ...
;         typedef __attribute__((address_space(4))) const Params* KP;
;         KP kp = (KP)__builtin_amdgcn_kernarg_segment_ptr();
;         int wvi = wv0; asm volatile("" : "+s"(wvi));
;         unsigned ones = ~0u; asm volatile("" : "+s"(ones));
;         int tid = wvi * 64 + (int)__builtin_amdgcn_mbcnt_hi(ones, __builtin_amdgcn_mbcnt_lo(ones, 0u)), G = G0, bx = bx0;
;         asm volatile("" : "+v"(tid), "+s"(G), "+s"(bx), "+s"(kp) :: "memory");
;         const Params& P = *(const Params*)kp; unsigned char* ws = P.ws;
;         PG8_LAS unsigned char* ldsl = (PG8_LAS unsigned char*)lds_raw; asm volatile("" : "+v"(ldsl));
;         unsigned char* lds = (unsigned char*)ldsl;
;         float* MOD = (float*)(ws + OFF_MOD);
_Z8mega_fwd6Params:
	v_and_b32_e32 v1, 0x3ff, v0
	v_writelane_b32 v255, s0, 0
	s_load_dwordx2 s[12:13], s[0:1], 0xb8
	s_movk_i32 s3, 0x3ff
	v_writelane_b32 v255, s1, 1
	v_readfirstlane_b32 s0, v1
	s_waitcnt lgkmcnt(0)
	s_cmp_ge_i32 s12, s13
	s_cbranch_scc1 .LBB0_1067
	v_readlane_b32 s6, v255, 0
	v_readlane_b32 s7, v255, 1
	s_load_dword s72, s[6:7], 0xc0
	s_load_dwordx2 s[4:5], s[6:7], 0xb0
	s_add_u32 s6, s6, 0xc0
	s_addc_u32 s7, s7, 0
	v_writelane_b32 v255, s6, 2
	s_lshr_b32 s71, s0, 6
	s_add_i32 s0, s12, 1
	v_writelane_b32 v255, s7, 3
	s_waitcnt lgkmcnt(0)
	s_add_u32 s14, s4, 0x300000
	v_writelane_b32 v255, s0, 4
	s_addc_u32 s15, s5, 0
	s_lshl_b32 s0, s2, 3
	s_lshl_b32 s95, s72, 3
	s_lshl_b32 s16, s72, 9
	s_lshl_b32 s18, s72, 5
	s_cmpk_lt_i32 s2, 0x100
	v_writelane_b32 v255, s0, 5
	s_cselect_b64 s[0:1], -1, 0
	v_writelane_b32 v255, s0, 6
	v_lshrrev_b32_e32 v2, 20, v0
	v_lshrrev_b32_e32 v0, 10, v0
	v_writelane_b32 v255, s1, 7
	s_lshl_b32 s0, s2, 9
	v_writelane_b32 v255, s0, 8
	s_lshl_b32 s0, s72, 4
	v_writelane_b32 v255, s0, 9
	s_lshl_b32 s0, s2, 10
	v_writelane_b32 v255, s0, 10
	s_mov_b32 s0, 0
	v_or_b32_e32 v0, v0, v2
	v_writelane_b32 v255, s0, 11
	v_cmp_eq_u32_e64 s[0:1], 0, v1
	v_and_or_b32 v0, v0, s3, v1
	s_mov_b32 s70, s12
	v_writelane_b32 v255, s0, 12
	s_ashr_i32 s17, s16, 31
	s_lshl_b64 s[20:21], s[16:17], 4
	v_writelane_b32 v255, s1, 13
	v_cmp_eq_u32_e64 s[0:1], 0, v0
	s_ashr_i32 s19, s18, 31
	s_lshl_b64 s[22:23], s[18:19], 11
	v_writelane_b32 v255, s0, 14
	s_lshl_b64 s[24:25], s[18:19], 12
	v_mbcnt_lo_u32_b32 v2, -1, 0
	v_writelane_b32 v255, s1, 15
	v_writelane_b32 v255, s12, 16
	v_mov_b32_e32 v165, 0
	s_movk_i32 s85, 0x4000
	v_writelane_b32 v255, s13, 17
	v_writelane_b32 v255, s71, 18
	v_writelane_b32 v255, s14, 19
	s_movk_i32 s56, 0x90
	v_mov_b32_e32 v169, 0x358637bd
	v_writelane_b32 v255, s15, 20
	v_writelane_b32 v255, s16, 21
	s_mov_b32 s57, 0x800000
	s_mov_b32 s88, 0x3fb8aa3b
	v_writelane_b32 v255, s17, 22
	v_writelane_b32 v255, s18, 23
	s_movk_i32 s89, 0x7fff
	s_mov_b32 s64, 0xc2fc0000
	v_writelane_b32 v255, s19, 24
	v_writelane_b32 v255, s20, 25
	s_mov_b32 s79, 0xc2ce8ed0
	s_mov_b32 s54, 0x42b17218
	v_writelane_b32 v255, s21, 26
	v_writelane_b32 v255, s22, 27
	s_movk_i32 s65, 0x110
	s_movk_i32 s62, 0x840
	v_writelane_b32 v255, s23, 28
	v_writelane_b32 v255, s24, 29
	v_mov_b32_e32 v204, 0x1a0000
	s_mov_b32 s58, 0xbfb8aa3b
	s_mov_b32 s59, 0x42ce8ed0
	s_mov_b32 s55, 0xc2b17218
	v_mbcnt_hi_u32_b32 v206, -1, v2
	v_mov_b32_e32 v207, 0xf149f2ca
	v_mov_b32_e32 v254, 0x42800000
	v_mov_b32_e32 v205, 0x41b17218
	v_mov_b32_e32 v210, 0x7f800000
	v_not_b32_e32 v211, 63
	s_mov_b32 s68, 0x9000
	s_movk_i32 s69, 0x1600
	s_movk_i32 s60, 0x5800
	s_movk_i32 s61, 0x7440
	s_movk_i32 s81, 0x3fff
	s_mov_b32 s94, 0x38e38e39
	s_mov_b32 s67, 0
	s_mov_b64 s[74:75], 0x20000
	s_mov_b64 s[76:77], 0x80
	s_mov_b32 s78, 0x3c800000
	s_mov_b32 s80, 0x3e000000
	s_mov_b64 s[82:83], 0x60000
	s_mov_b32 s84, 0x358637bd
	s_mov_b64 s[86:87], 0x10000
	s_mov_b64 s[90:91], 0x1000
	v_writelane_b32 v255, s25, 30
	s_mov_b32 s98, 0
	s_branch .LBB0_4

; DI void convert_ffn(const Params& p, int l, int which  , unsigned char* lds, int tid, int gw, int NGW) {
;     const int lane = tid & 63, wave = tid >> 6; float* scr = (float*)(lds + wave * 16384);
;     const float* w13 = p.in[which == 0 ? 5 : 19] + (size_t)l * DM * 2 * DFF; const float* w2 = p.in[which == 0 ? 6 : 20] + (size_t)l * DFF * DM;
;     constexpr int I13 = 16 * 176, I2 = 44 * 32;
;     for (int it = gw; it < I13 + I2; it += NGW) {
;         if (it < I13) conv_item(w13, DM, 2 * DFF, (bf16_t*)(p.ws + OFF_W13T), 1, scr, it, lane);
;         else conv_item(w2, DFF, DM, (bf16_t*)(p.ws + OFF_W2T), 0, scr, it - I13, lane); }
; __global__ void __launch_bounds__(512, 2) mega_fwd(Params p) {
;     ...
;         if (s == 0 || s == 3 || s == 9) { phase_prep(P, l, s == 0 ? 0 : (s == 3 ? 1 : 2), xsrc, lds, tid); }
.LBB0_790:
	s_cmpk_lg_u32 s72, 0x100
	s_cbranch_scc1 .Lhlp_no
	s_cmp_lt_u32 s2, 0x80
	s_cbranch_scc1 .Lhlp_no
	s_cmp_eq_u32 s63, 1
	s_cbranch_scc1 .Lhlp_mix
	s_cmp_eq_u32 s63, 4
	s_cbranch_scc0 .Lhlp_no
	s_mov_b32 s99, 9
	s_branch .Lhlp_go
.Lhlp_mix:
	s_mov_b32 s99, 3
.Lhlp_go:
	s_mov_b32 s98, s63
	s_mov_b32 s63, s99
	s_mov_b32 s100, s95
	s_movk_i32 s95, 0x400
	v_readlane_b32 s101, v255, 5
	s_sub_i32 s99, s2, 0x80
	s_lshl_b32 s99, s99, 3
	s_nop 1
	v_writelane_b32 v255, s99, 5
	s_movk_i32 s99, 0x800
	s_nop 1
	v_writelane_b32 v255, s99, 9
	s_mov_b32 s99, 0x10000
	s_nop 1
	v_writelane_b32 v255, s99, 21
	s_mov_b32 s99, 0x100000
	s_nop 1
	v_writelane_b32 v255, s99, 25
	s_nop 1
	v_readlane_b32 s0, v255, 0
	v_readlane_b32 s1, v255, 1
	s_mov_b64 s[26:27], -1
.Lhlp_no:
	s_andn2_b64 vcc, exec, s[26:27]
	s_cbranch_vccnz .LBB0_1000
	s_cmp_eq_u32 s63, 0
	s_cselect_b64 s[6:7], -1, 0
	s_cmp_eq_u32 s63, 3
	v_ashrrev_i32_e32 v0, 6, v166
	v_readlane_b32 s4, v255, 5
	s_cselect_b64 s[8:9], -1, 0
	s_cmp_lg_u32 s63, 3
	s_waitcnt vmcnt(0)
	v_add_u32_e32 v64, s4, v0
	s_mov_b64 s[10:11], -1
	s_movk_i32 s31, 0xaff
	s_cbranch_scc0 .LBB0_888
	s_cmp_eq_u32 s98, 0
	s_cbranch_scc0 .Lhlp_nsk9
	s_cmp_eq_u32 s63, 9
	s_cbranch_scc0 .Lhlp_nsk9
	s_cmpk_lg_u32 s72, 0x100
	s_cbranch_scc1 .Lhlp_nsk9
	s_mov_b64 s[10:11], 0
	s_branch .LBB0_887
.Lhlp_nsk9:
	s_movk_i32 s4, 0x1080
	v_cmp_gt_i32_e32 vcc, s4, v64
	s_and_saveexec_b64 s[10:11], vcc
	s_cbranch_execz .LBB0_887
	s_and_b64 s[4:5], s[6:7], exec
	s_cselect_b32 s4, 40, 0x98
	s_add_u32 s4, s0, s4
	s_addc_u32 s5, s1, 0
	s_load_dwordx2 s[4:5], s[4:5], 0x0
	s_mul_i32 s12, s20, 0x1600000
	s_mul_hi_i32 s13, s20, 0x1600000
	v_lshlrev_b32_e32 v0, 8, v166
	v_and_b32_e32 v5, 31, v166
	s_waitcnt lgkmcnt(0)
	s_add_u32 s12, s4, s12
	s_addc_u32 s13, s5, s13
	s_and_b64 s[4:5], s[6:7], exec
	s_cselect_b32 s4, 48, 0xa0
	s_add_u32 s4, s0, s4
	s_addc_u32 s5, s1, 0
	s_load_dwordx2 s[4:5], s[4:5], 0x0
	v_and_b32_e32 v0, 0xffffc000, v0
	v_bfe_u32 v20, v166, 5, 1
	v_add_u32_e32 v0, v168, v0
	v_mul_u32_u24_e32 v1, 0x84, v20
	v_lshlrev_b32_e32 v2, 2, v5
	v_add3_u32 v21, v0, v1, v2
	v_lshlrev_b32_e32 v1, 3, v166
	s_mul_i32 s14, s20, 0xb00000
	v_bfe_u32 v22, v166, 3, 3
	v_and_b32_e32 v1, 56, v1
	s_mul_hi_i32 s15, s20, 0xb00000
	s_waitcnt lgkmcnt(0)
	s_add_u32 s14, s4, s14
	v_mul_u32_u24_e32 v2, 0x84, v1
	v_lshlrev_b32_e32 v3, 2, v22
	v_lshlrev_b32_e32 v164, 1, v1
	s_addc_u32 s15, s5, s15
	v_add3_u32 v23, v0, v2, v3
	v_lshl_add_u64 v[2:3], s[96:97], 0, v[164:165]
	s_mov_b64 s[4:5], 0x1400000
	v_lshlrev_b32_e32 v4, 1, v22
	v_lshl_add_u64 v[0:1], v[2:3], 0, s[4:5]
	s_mov_b64 s[4:5], 0x900000
	v_lshl_or_b32 v4, v64, 6, v4
	v_mov_b32_e32 v6, 0x1ea00
	v_or_b32_e32 v24, 8, v22
	v_or_b32_e32 v25, 16, v22
	v_or_b32_e32 v26, 24, v22
	v_lshl_add_u64 v[2:3], v[2:3], 0, s[4:5]
	v_lshlrev_b32_e32 v27, 5, v64
	s_lshl_b32 s28, s95, 5
	v_add_u32_e32 v4, 0x7fffea30, v4
	s_lshl_b32 s29, s95, 6
	v_lshl_add_u32 v28, v64, 1, v6
	s_lshl_b32 s30, s95, 1
	s_mov_b64 s[16:17], 0
	v_mov_b32_e32 v29, v64
	s_branch .LBB0_797

; DI void convert_mix(const Params& p, int l, unsigned char* lds, int tid, int gw, int NGW) {
;     unsigned zu = 0u; asm volatile("" : "+v"(zu));
;     const int lane = tid & 63, wave = tid >> 6; float* scr = (float*)(lds + wave * 16384);
;     const float* win = p.in[8] + (size_t)l * DM * 7440; const float* wb = p.in[16] + (size_t)l * 3 * 512 * DM; const float* wo = p.in[17] + (size_t)l * DM * DM;
;     constexpr int IIN = 16 * 233, IB = 8 * 32, IO = 16 * 32;
;     for (int it = gw; it < IIN + 3 * IB + IO; it += NGW) { int r = it;
;         if (r < IIN) { conv_item(win, DM, 7440, (bf16_t*)(p.ws + OFF_WINT), 2, scr, r, lane); continue; } r -= IIN;
;         if (r < 3 * IB) { const int g = r / IB; conv_item(wb + (size_t)g * 512 * DM, 512, DM, (bf16_t*)(p.ws + OFF_WBT) + (size_t)g * DM * 512, 0, scr, r % IB, lane); continue; } r -= 3 * IB;
;         conv_item(wo, DM, DM, (bf16_t*)(p.ws + OFF_WOT), 0, scr, r, lane); }
.LBB0_888:
	s_mov_b64 s[12:13], 18
	s_cmp_eq_u32 s98, 0
	s_cbranch_scc0 .Lhlp_nsk3
	s_cmp_eq_u32 s63, 3
	s_cbranch_scc0 .Lhlp_nsk3
	s_cmpk_lg_u32 s72, 0x100
	s_cbranch_scc1 .Lhlp_nsk3
	s_mov_b64 s[10:11], 0
	s_mov_b64 s[12:13], 7
.Lhlp_nsk3:
	s_andn2_b64 vcc, exec, s[10:11]
	v_and_b32_e32 v20, 63, v166
	v_readlane_b32 s36, v255, 9
	s_movk_i32 s37, 0x1d10
	s_cbranch_vccnz .LBB0_996
	s_movk_i32 s4, 0x1390
	v_mov_b32_e32 v0, v165
	v_cmp_gt_i32_e32 vcc, s4, v64
	s_and_saveexec_b64 s[10:11], vcc
	s_cbranch_execz .LBB0_992
	s_load_dwordx2 s[4:5], s[0:1], 0x40
	s_load_dwordx4 s[24:27], s[0:1], 0x80
	v_lshlrev_b32_e32 v1, 8, v166
	s_mul_i32 s12, s20, 0x1d10000
	v_and_b32_e32 v1, 0xffffc000, v1
	s_mul_hi_i32 s13, s20, 0x1d10000
	s_waitcnt lgkmcnt(0)
	s_add_u32 s12, s4, s12
	v_add_u32_e32 v2, v168, v1
	v_and_b32_e32 v1, 31, v166
	v_lshrrev_b32_e32 v21, 5, v20
	s_addc_u32 s13, s5, s13
	s_mul_i32 s4, s20, 0x600000
	v_mul_u32_u24_e32 v3, 0x84, v21
	v_lshlrev_b32_e32 v4, 2, v1
	s_mul_hi_i32 s15, s20, 0x600000
	s_add_u32 s14, s24, s4
	v_add3_u32 v22, v2, v3, v4
	v_lshlrev_b32_e32 v3, 3, v20
	s_addc_u32 s15, s25, s15
	s_lshl_b64 s[4:5], s[20:21], 22
	v_lshrrev_b32_e32 v23, 3, v20
	v_and_b32_e32 v6, 56, v3
	s_add_u32 s16, s26, s4
	v_mul_u32_u24_e32 v3, 0x84, v6
	v_lshlrev_b32_e32 v4, 2, v23
	v_lshlrev_b32_e32 v164, 1, v6
	s_addc_u32 s17, s27, s5
	v_add3_u32 v24, v2, v3, v4
	v_lshl_add_u64 v[4:5], s[96:97], 0, v[164:165]
	s_mov_b64 s[4:5], 0x700000
	v_lshl_add_u64 v[2:3], v[4:5], 0, s[4:5]
	s_add_u32 s22, s96, 0x400000
	s_mov_b64 s[4:5], 0x3980000
	v_mov_b32_e32 v7, 0xffffdce0
	v_or_b32_e32 v25, 8, v23
	v_or_b32_e32 v26, 16, v23
	v_or_b32_e32 v27, 24, v23
	s_addc_u32 s23, s97, 0
	v_lshl_add_u64 v[4:5], v[4:5], 0, s[4:5]
	v_lshlrev_b32_e32 v28, 5, v64
	s_lshl_b32 s21, s95, 5
	v_lshl_add_u32 v29, v64, 1, v7
	s_lshl_b32 s33, s95, 1
	s_mov_b64 s[24:25], 0
	v_lshlrev_b32_e32 v6, 1, v6
	v_mov_b32_e32 v30, v64
	s_branch .LBB0_895

; DI void phase_prep(const Params& p, int l, int which  , const float* xsrc, unsigned char* lds, int tid) {
;     const int lane = tid & 63, wave = tid >> 6, gw = blockIdx.x * 8 + wave, NGW = gridDim.x * 8;
;     if (which == 1) convert_mix(p, l, lds, tid, gw, NGW); else convert_ffn(p, l, which, lds, tid, gw, NGW);
;     const float* gain = p.in[which == 0 ? 4 : (which == 1 ? 7 : 18)] + l * DM;
;     modulate_rows(xsrc, gain, (const float*)(p.ws + OFF_MOD) + (size_t)l * 8 * NMODW, which, (bf16_t*)(p.ws + OFF_U), gw, NGW, lane);
; }
.LBB0_996:
	s_cmp_eq_u32 s98, 0
	s_cbranch_scc1 .Lhlp_cont
	s_mov_b32 s63, s98
	s_mov_b32 s98, 0
	s_mov_b32 s95, s100
	s_nop 1
	v_writelane_b32 v255, s101, 5
	s_lshl_b32 s99, s72, 4
	s_nop 1
	v_writelane_b32 v255, s99, 9
	s_lshl_b32 s99, s72, 9
	s_nop 1
	v_writelane_b32 v255, s99, 21
	s_lshl_b32 s99, s72, 13
	s_nop 1
	v_writelane_b32 v255, s99, 25
	s_branch .LBB0_1000

; __global__ void __launch_bounds__(512, 2) mega_fwd(Params p) {
;     extern __shared__ __attribute__((aligned(16))) unsigned char lds_raw[];
	.amdhsa_kernel _Z8mega_fwd6Params
		.amdhsa_group_segment_fixed_size 0
		.amdhsa_private_segment_fixed_size 0
		.amdhsa_kernarg_size 448
		.amdhsa_user_sgpr_count 2
		.amdhsa_user_sgpr_dispatch_ptr 0
		.amdhsa_user_sgpr_queue_ptr 0
		.amdhsa_user_sgpr_kernarg_segment_ptr 1
		.amdhsa_user_sgpr_dispatch_id 0
		.amdhsa_user_sgpr_kernarg_preload_length 0
		.amdhsa_user_sgpr_kernarg_preload_offset 0
		.amdhsa_user_sgpr_private_segment_size 0
		.amdhsa_uses_dynamic_stack 0
		.amdhsa_enable_private_segment 0
		.amdhsa_system_sgpr_workgroup_id_x 1
		.amdhsa_system_sgpr_workgroup_id_y 0
		.amdhsa_system_sgpr_workgroup_id_z 0
		.amdhsa_system_sgpr_workgroup_info 0
		.amdhsa_system_vgpr_workitem_id 2
		.amdhsa_next_free_vgpr 256
		.amdhsa_next_free_sgpr 102
		.amdhsa_accum_offset 256
		.amdhsa_reserve_vcc 1
		.amdhsa_float_round_mode_32 0
		.amdhsa_float_round_mode_16_64 0
		.amdhsa_float_denorm_mode_32 3
		.amdhsa_float_denorm_mode_16_64 3
		.amdhsa_dx10_clamp 1
		.amdhsa_ieee_mode 1
		.amdhsa_fp16_overflow 0
		.amdhsa_tg_split 0
		.amdhsa_exception_fp_ieee_invalid_op 0
		.amdhsa_exception_fp_denorm_src 0
		.amdhsa_exception_fp_ieee_div_zero 0
		.amdhsa_exception_fp_ieee_overflow 0
		.amdhsa_exception_fp_ieee_underflow 0
		.amdhsa_exception_fp_ieee_inexact 0
		.amdhsa_exception_int_div_zero 0
	.end_amdhsa_kernel

; __global__ void __launch_bounds__(512, 2) mega_fwd(Params p) {
;     extern __shared__ __attribute__((aligned(16))) unsigned char lds_raw[];
amdhsa.kernels:
  - .agpr_count:     0
    .args:
      - .offset:         0
        .size:           192
        .value_kind:     by_value
      - .offset:         192
        .size:           4
        .value_kind:     hidden_block_count_x
      - .offset:         196
        .size:           4
        .value_kind:     hidden_block_count_y
      - .offset:         200
        .size:           4
        .value_kind:     hidden_block_count_z
      - .offset:         204
        .size:           2
        .value_kind:     hidden_group_size_x
      - .offset:         206
        .size:           2
        .value_kind:     hidden_group_size_y
      - .offset:         208
        .size:           2
        .value_kind:     hidden_group_size_z
      - .offset:         210
        .size:           2
        .value_kind:     hidden_remainder_x
      - .offset:         212
        .size:           2
        .value_kind:     hidden_remainder_y
      - .offset:         214
        .size:           2
        .value_kind:     hidden_remainder_z
      - .offset:         232
        .size:           8
        .value_kind:     hidden_global_offset_x
      - .offset:         240
        .size:           8
        .value_kind:     hidden_global_offset_y
      - .offset:         248
        .size:           8
        .value_kind:     hidden_global_offset_z
      - .offset:         256
        .size:           2
        .value_kind:     hidden_grid_dims
      - .offset:         280
        .size:           8
        .value_kind:     hidden_multigrid_sync_arg
      - .offset:         312
        .size:           4
        .value_kind:     hidden_dynamic_lds_size
    .group_segment_fixed_size: 0
    .kernarg_segment_align: 8
    .kernarg_segment_size: 448
    .language:       OpenCL C
    .language_version:
      - 2
      - 0
    .max_flat_workgroup_size: 512
    .name:           _Z8mega_fwd6Params
    .private_segment_fixed_size: 0
    .sgpr_count:     108
    .sgpr_spill_count: 71
    .symbol:         _Z8mega_fwd6Params.kd
    .uniform_work_group_size: 1
    .uses_dynamic_stack: false
    .vgpr_count:     256
    .vgpr_spill_count: 0
    .wavefront_size: 64
